# v47 + LN1/SGU LayerNorm-parameter staging remainder loops: loads of an iteration issued together, one wait
# speedup vs baseline: 1.0031x; 1.0031x over previous
; #define LAS __attribute__((address_space(3)))
; __device__ __forceinline__ void sgu_pool_chunk(KArgs A, int l, int chunk, LAS unsigned char* lds) {
;     ...
;     LAS float* bL = gL + D_; LAS float* sbL = bL + D_;
;     for (int i = tid; i < D_; i += 512) { gL[i] = lng[i]; bL[i] = lnb[i]; sbL[i] = sb[i]; }
.LBB0_327:
	global_load_dword v8, v[4:5], off
	global_load_dword v9, v[2:3], off
	global_load_dword v14, v[0:1], off
	v_add_u32_e32 v6, 0x200, v6
	v_cmp_lt_i32_e32 vcc, s73, v6
	v_lshl_add_u64 v[2:3], v[2:3], 0, s[54:55]
	v_lshl_add_u64 v[4:5], v[4:5], 0, s[54:55]
	v_lshl_add_u64 v[0:1], v[0:1], 0, s[54:55]
	s_or_b64 s[4:5], vcc, s[4:5]
	s_waitcnt vmcnt(1)
	ds_write2st64_b32 v7, v8, v9 offset1:16
	s_waitcnt vmcnt(0)
	ds_write_b32 v7, v14 offset:8192
	v_add_u32_e32 v7, 0x800, v7
	s_andn2_b64 exec, exec, s[4:5]
	s_cbranch_execnz .LBB0_327

; #define LAS __attribute__((address_space(3)))
; __device__ __forceinline__ void stage_ln_params(const float* g, const float* b, LAS float* gL, LAS float* bL, int tid) {
;     for (int i = tid; i < D_; i += 512) { gL[i] = g[i]; bL[i] = b[i]; }
; }
.LBB0_580:
	global_load_dword v7, v[2:3], off
	global_load_dword v8, v[4:5], off
	v_add_u32_e32 v1, 0x200, v1
	v_cmp_lt_i32_e32 vcc, s73, v1
	v_lshl_add_u64 v[2:3], v[2:3], 0, s[54:55]
	v_lshl_add_u64 v[4:5], v[4:5], 0, s[54:55]
	s_or_b64 s[4:5], vcc, s[4:5]
	v_add_u32_e32 v6, 0xfffff000, v6
	s_waitcnt vmcnt(0)
	ds_write_b32 v6, v7
	ds_write_b32 v6, v8 offset:4096
	v_add_u32_e32 v6, 0x1800, v6
	s_andn2_b64 exec, exec, s[4:5]
	s_cbranch_execnz .LBB0_580
